# MFMA order variant: n-major, m, k-inner with serpentine k (adjacent pairs share srcA at pair boundary); accumulation order of half the tiles k1 then k0
# speedup vs baseline: 1.0239x; 1.0008x over previous
.LBB0_32:
	s_add_u32 s28, s54, 0xfff80080
	s_addc_u32 s29, s55, -1
	s_add_i32 s30, 0, 0x10000
	s_cmp_eq_u32 s27, 28
	s_cselect_b32 s79, s13, s29
	s_cselect_b32 s78, s16, s28
	s_cselect_b32 s69, s9, s26
	s_cselect_b32 s68, s24, s25
	s_add_i32 s31, 0, 0x14000
	v_add_u32_e32 v142, s30, v184
	v_add_u32_e32 v172, s31, v184
	ds_read_b128 v[130:133], v142
	ds_read_b128 v[134:137], v142 offset:1024
	ds_read_b128 v[138:141], v142 offset:2048
	ds_read_b128 v[142:145], v142 offset:3072
	ds_read_b128 v[146:149], v172
	ds_read_b128 v[150:153], v172 offset:1024
	ds_read_b128 v[154:157], v172 offset:2048
	ds_read_b128 v[172:175], v172 offset:3072
	v_lshl_add_u64 v[212:213], s[54:55], 0, v[166:167]
	s_add_i32 m0, s42, 0xc000
	ds_read_b128 v[176:179], v186
	ds_read_b128 v[180:183], v186 offset:1024
	ds_read_b128 v[188:191], v186 offset:2048
	ds_read_b128 v[192:195], v186 offset:3072
	ds_read_b128 v[196:199], v186 offset:4096
	ds_read_b128 v[200:203], v186 offset:5120
	ds_read_b128 v[204:207], v186 offset:6144
	ds_read_b128 v[208:211], v186 offset:7168
	global_load_lds_dwordx4 v[212:213], off
	v_lshl_add_u64 v[212:213], s[54:55], 0, v[168:169]
	s_add_i32 m0, s42, 0xe000
	s_nop 0
	global_load_lds_dwordx4 v[212:213], off
	s_waitcnt vmcnt(8)
	s_waitcnt lgkmcnt(0)
	s_barrier
	s_setprio 1
	s_waitcnt lgkmcnt(0)
	v_mfma_f32_16x16x32_bf16 v[126:129], v[130:133], v[176:179], v[126:129]
	v_mfma_f32_16x16x32_bf16 v[126:129], v[134:137], v[180:183], v[126:129]
	v_mfma_f32_16x16x32_bf16 v[110:113], v[134:137], v[192:195], v[110:113]
	v_mfma_f32_16x16x32_bf16 v[110:113], v[130:133], v[188:191], v[110:113]
	v_mfma_f32_16x16x32_bf16 v[94:97], v[130:133], v[196:199], v[94:97]
	v_mfma_f32_16x16x32_bf16 v[94:97], v[134:137], v[200:203], v[94:97]
	v_mfma_f32_16x16x32_bf16 v[78:81], v[134:137], v[208:211], v[78:81]
	v_mfma_f32_16x16x32_bf16 v[78:81], v[130:133], v[204:207], v[78:81]
	v_mfma_f32_16x16x32_bf16 v[122:125], v[138:141], v[176:179], v[122:125]
	v_mfma_f32_16x16x32_bf16 v[122:125], v[142:145], v[180:183], v[122:125]
	v_mfma_f32_16x16x32_bf16 v[106:109], v[142:145], v[192:195], v[106:109]
	v_mfma_f32_16x16x32_bf16 v[106:109], v[138:141], v[188:191], v[106:109]
	v_mfma_f32_16x16x32_bf16 v[90:93], v[138:141], v[196:199], v[90:93]
	v_mfma_f32_16x16x32_bf16 v[90:93], v[142:145], v[200:203], v[90:93]
	v_mfma_f32_16x16x32_bf16 v[74:77], v[142:145], v[208:211], v[74:77]
	v_mfma_f32_16x16x32_bf16 v[74:77], v[138:141], v[204:207], v[74:77]
	s_setprio 0
	s_setprio 1
	v_mfma_f32_16x16x32_bf16 v[118:121], v[146:149], v[176:179], v[118:121]
	v_mfma_f32_16x16x32_bf16 v[118:121], v[150:153], v[180:183], v[118:121]
	v_mfma_f32_16x16x32_bf16 v[102:105], v[150:153], v[192:195], v[102:105]
	v_mfma_f32_16x16x32_bf16 v[102:105], v[146:149], v[188:191], v[102:105]
	v_mfma_f32_16x16x32_bf16 v[86:89], v[146:149], v[196:199], v[86:89]
	v_mfma_f32_16x16x32_bf16 v[86:89], v[150:153], v[200:203], v[86:89]
	v_mfma_f32_16x16x32_bf16 v[70:73], v[150:153], v[208:211], v[70:73]
	v_mfma_f32_16x16x32_bf16 v[70:73], v[146:149], v[204:207], v[70:73]
	v_mfma_f32_16x16x32_bf16 v[114:117], v[154:157], v[176:179], v[114:117]
	v_mfma_f32_16x16x32_bf16 v[114:117], v[172:175], v[180:183], v[114:117]
	v_mfma_f32_16x16x32_bf16 v[98:101], v[172:175], v[192:195], v[98:101]
	v_mfma_f32_16x16x32_bf16 v[98:101], v[154:157], v[188:191], v[98:101]
	v_mfma_f32_16x16x32_bf16 v[82:85], v[154:157], v[196:199], v[82:85]
	v_mfma_f32_16x16x32_bf16 v[82:85], v[172:175], v[200:203], v[82:85]
	v_mfma_f32_16x16x32_bf16 v[66:69], v[172:175], v[208:211], v[66:69]
	v_mfma_f32_16x16x32_bf16 v[66:69], v[154:157], v[204:207], v[66:69]
	s_setprio 0
	s_barrier
	s_add_i32 s28, s30, s11
	v_lshl_add_u64 v[212:213], s[68:69], 0, v[160:161]
	s_mov_b32 m0, s28
	ds_read_b128 v[176:179], v186 offset:16384
	ds_read_b128 v[180:183], v186 offset:17408
	ds_read_b128 v[188:191], v186 offset:18432
	ds_read_b128 v[192:195], v186 offset:19456
	ds_read_b128 v[196:199], v186 offset:20480
	ds_read_b128 v[200:203], v186 offset:21504
	ds_read_b128 v[204:207], v186 offset:22528
	ds_read_b128 v[208:211], v186 offset:23552
	global_load_lds_dwordx4 v[212:213], off
	s_add_i32 m0, s28, 0x2000
	s_add_u32 s28, s68, 0x80000
	v_lshl_add_u64 v[232:233], s[68:69], 0, v[164:165]
	s_addc_u32 s29, s69, 0
	s_add_i32 s30, s31, s11
	global_load_lds_dwordx4 v[232:233], off
	v_lshl_add_u64 v[234:235], s[28:29], 0, v[160:161]
	s_mov_b32 m0, s30
	v_lshl_add_u64 v[236:237], s[78:79], 0, v[162:163]
	global_load_lds_dwordx4 v[234:235], off
	v_lshl_add_u64 v[234:235], s[28:29], 0, v[164:165]
	s_add_i32 m0, s30, 0x2000
	s_nop 0
	global_load_lds_dwordx4 v[234:235], off
	v_lshl_add_u64 v[234:235], s[78:79], 0, v[158:159]
	s_mov_b32 m0, s42
	s_nop 0
	global_load_lds_dwordx4 v[234:235], off
	s_mov_b32 m0, s57
	s_nop 0
	global_load_lds_dwordx4 v[236:237], off
	s_waitcnt vmcnt(8)
	s_waitcnt lgkmcnt(0)
	s_barrier
	s_setprio 1
	s_waitcnt lgkmcnt(0)
	v_mfma_f32_16x16x32_bf16 v[62:65], v[130:133], v[176:179], v[62:65]
	v_mfma_f32_16x16x32_bf16 v[62:65], v[134:137], v[180:183], v[62:65]
	v_mfma_f32_16x16x32_bf16 v[46:49], v[134:137], v[192:195], v[46:49]
	v_mfma_f32_16x16x32_bf16 v[46:49], v[130:133], v[188:191], v[46:49]
	v_mfma_f32_16x16x32_bf16 v[30:33], v[130:133], v[196:199], v[30:33]
	v_mfma_f32_16x16x32_bf16 v[30:33], v[134:137], v[200:203], v[30:33]
	v_mfma_f32_16x16x32_bf16 v[14:17], v[134:137], v[208:211], v[14:17]
	v_mfma_f32_16x16x32_bf16 v[14:17], v[130:133], v[204:207], v[14:17]
	v_mfma_f32_16x16x32_bf16 v[58:61], v[138:141], v[176:179], v[58:61]
	v_mfma_f32_16x16x32_bf16 v[58:61], v[142:145], v[180:183], v[58:61]
	v_mfma_f32_16x16x32_bf16 v[42:45], v[142:145], v[192:195], v[42:45]
	v_mfma_f32_16x16x32_bf16 v[42:45], v[138:141], v[188:191], v[42:45]
	v_mfma_f32_16x16x32_bf16 v[26:29], v[138:141], v[196:199], v[26:29]
	v_mfma_f32_16x16x32_bf16 v[26:29], v[142:145], v[200:203], v[26:29]
	v_mfma_f32_16x16x32_bf16 v[10:13], v[142:145], v[208:211], v[10:13]
	v_mfma_f32_16x16x32_bf16 v[10:13], v[138:141], v[204:207], v[10:13]
	s_setprio 0
	s_setprio 1
	v_mfma_f32_16x16x32_bf16 v[54:57], v[146:149], v[176:179], v[54:57]
	v_mfma_f32_16x16x32_bf16 v[54:57], v[150:153], v[180:183], v[54:57]
	v_mfma_f32_16x16x32_bf16 v[38:41], v[150:153], v[192:195], v[38:41]
	v_mfma_f32_16x16x32_bf16 v[38:41], v[146:149], v[188:191], v[38:41]
	v_mfma_f32_16x16x32_bf16 v[22:25], v[146:149], v[196:199], v[22:25]
	v_mfma_f32_16x16x32_bf16 v[22:25], v[150:153], v[200:203], v[22:25]
	v_mfma_f32_16x16x32_bf16 v[6:9], v[150:153], v[208:211], v[6:9]
	v_mfma_f32_16x16x32_bf16 v[6:9], v[146:149], v[204:207], v[6:9]
	v_mfma_f32_16x16x32_bf16 v[50:53], v[154:157], v[176:179], v[50:53]
	v_mfma_f32_16x16x32_bf16 v[50:53], v[172:175], v[180:183], v[50:53]
	v_mfma_f32_16x16x32_bf16 v[34:37], v[172:175], v[192:195], v[34:37]
	v_mfma_f32_16x16x32_bf16 v[34:37], v[154:157], v[188:191], v[34:37]
	v_mfma_f32_16x16x32_bf16 v[18:21], v[154:157], v[196:199], v[18:21]
	v_mfma_f32_16x16x32_bf16 v[18:21], v[172:175], v[200:203], v[18:21]
	v_mfma_f32_16x16x32_bf16 v[2:5], v[172:175], v[208:211], v[2:5]
	v_mfma_f32_16x16x32_bf16 v[2:5], v[154:157], v[204:207], v[2:5]
	s_setprio 0
	s_barrier
	s_add_i32 s30, 0, 0x18000
	s_add_i32 s31, 0, 0x1c000
	v_add_u32_e32 v142, s30, v184
	v_add_u32_e32 v172, s31, v184
	ds_read_b128 v[130:133], v142
	ds_read_b128 v[134:137], v142 offset:1024
	ds_read_b128 v[138:141], v142 offset:2048
	ds_read_b128 v[142:145], v142 offset:3072
	ds_read_b128 v[146:149], v172
	ds_read_b128 v[150:153], v172 offset:1024
	ds_read_b128 v[154:157], v172 offset:2048
	ds_read_b128 v[172:175], v172 offset:3072
	s_add_u32 s28, s78, 0x80000
	s_addc_u32 s29, s79, 0
	s_mov_b32 m0, s67
	v_lshl_add_u64 v[238:239], s[28:29], 0, v[158:159]
	ds_read_b128 v[176:179], v186 offset:32768
	ds_read_b128 v[180:183], v186 offset:33792
	ds_read_b128 v[188:191], v186 offset:34816
	ds_read_b128 v[192:195], v186 offset:35840
	ds_read_b128 v[196:199], v186 offset:36864
	ds_read_b128 v[200:203], v186 offset:37888
	ds_read_b128 v[204:207], v186 offset:38912
	ds_read_b128 v[208:211], v186 offset:39936
	global_load_lds_dwordx4 v[238:239], off
	v_lshl_add_u64 v[238:239], s[28:29], 0, v[162:163]
	s_mov_b32 m0, s72
	s_nop 0
	global_load_lds_dwordx4 v[238:239], off
	s_waitcnt vmcnt(8)
	s_waitcnt lgkmcnt(0)
	s_barrier
	s_setprio 1
	s_waitcnt lgkmcnt(0)
	v_mfma_f32_16x16x32_bf16 v[126:129], v[130:133], v[176:179], v[126:129]
	v_mfma_f32_16x16x32_bf16 v[126:129], v[134:137], v[180:183], v[126:129]
	v_mfma_f32_16x16x32_bf16 v[110:113], v[134:137], v[192:195], v[110:113]
	v_mfma_f32_16x16x32_bf16 v[110:113], v[130:133], v[188:191], v[110:113]
	v_mfma_f32_16x16x32_bf16 v[94:97], v[130:133], v[196:199], v[94:97]
	v_mfma_f32_16x16x32_bf16 v[94:97], v[134:137], v[200:203], v[94:97]
	v_mfma_f32_16x16x32_bf16 v[78:81], v[134:137], v[208:211], v[78:81]
	v_mfma_f32_16x16x32_bf16 v[78:81], v[130:133], v[204:207], v[78:81]
	v_mfma_f32_16x16x32_bf16 v[122:125], v[138:141], v[176:179], v[122:125]
	v_mfma_f32_16x16x32_bf16 v[122:125], v[142:145], v[180:183], v[122:125]
	v_mfma_f32_16x16x32_bf16 v[106:109], v[142:145], v[192:195], v[106:109]
	v_mfma_f32_16x16x32_bf16 v[106:109], v[138:141], v[188:191], v[106:109]
	v_mfma_f32_16x16x32_bf16 v[90:93], v[138:141], v[196:199], v[90:93]
	v_mfma_f32_16x16x32_bf16 v[90:93], v[142:145], v[200:203], v[90:93]
	v_mfma_f32_16x16x32_bf16 v[74:77], v[142:145], v[208:211], v[74:77]
	v_mfma_f32_16x16x32_bf16 v[74:77], v[138:141], v[204:207], v[74:77]
	s_setprio 0
	s_setprio 1
	v_mfma_f32_16x16x32_bf16 v[118:121], v[146:149], v[176:179], v[118:121]
	v_mfma_f32_16x16x32_bf16 v[118:121], v[150:153], v[180:183], v[118:121]
	v_mfma_f32_16x16x32_bf16 v[102:105], v[150:153], v[192:195], v[102:105]
	v_mfma_f32_16x16x32_bf16 v[102:105], v[146:149], v[188:191], v[102:105]
	v_mfma_f32_16x16x32_bf16 v[86:89], v[146:149], v[196:199], v[86:89]
	v_mfma_f32_16x16x32_bf16 v[86:89], v[150:153], v[200:203], v[86:89]
	v_mfma_f32_16x16x32_bf16 v[70:73], v[150:153], v[208:211], v[70:73]
	v_mfma_f32_16x16x32_bf16 v[70:73], v[146:149], v[204:207], v[70:73]
	v_mfma_f32_16x16x32_bf16 v[114:117], v[154:157], v[176:179], v[114:117]
	v_mfma_f32_16x16x32_bf16 v[114:117], v[172:175], v[180:183], v[114:117]
	v_mfma_f32_16x16x32_bf16 v[98:101], v[172:175], v[192:195], v[98:101]
	v_mfma_f32_16x16x32_bf16 v[98:101], v[154:157], v[188:191], v[98:101]
	v_mfma_f32_16x16x32_bf16 v[82:85], v[154:157], v[196:199], v[82:85]
	v_mfma_f32_16x16x32_bf16 v[82:85], v[172:175], v[200:203], v[82:85]
	v_mfma_f32_16x16x32_bf16 v[66:69], v[172:175], v[208:211], v[66:69]
	v_mfma_f32_16x16x32_bf16 v[66:69], v[154:157], v[204:207], v[66:69]
	s_setprio 0
	s_barrier
	s_add_i32 s28, s30, s11
	v_lshl_add_u64 v[212:213], v[212:213], 0, s[62:63]
	s_mov_b32 m0, s28
	ds_read_b128 v[176:179], v186 offset:49152
	ds_read_b128 v[180:183], v186 offset:50176
	ds_read_b128 v[188:191], v186 offset:51200
	ds_read_b128 v[192:195], v186 offset:52224
	ds_read_b128 v[196:199], v186 offset:53248
	ds_read_b128 v[200:203], v186 offset:54272
	ds_read_b128 v[204:207], v186 offset:55296
	ds_read_b128 v[208:211], v186 offset:56320
	global_load_lds_dwordx4 v[212:213], off
	s_add_i32 m0, s28, 0x2000
	s_add_u32 s28, s68, 0x80080
	v_lshl_add_u64 v[212:213], v[232:233], 0, s[62:63]
	s_addc_u32 s29, s69, 0
	s_add_i32 s30, s31, s11
	global_load_lds_dwordx4 v[212:213], off
	v_lshl_add_u64 v[212:213], s[28:29], 0, v[160:161]
	s_mov_b32 m0, s30
	s_nop 0
	global_load_lds_dwordx4 v[212:213], off
	v_lshl_add_u64 v[212:213], s[28:29], 0, v[164:165]
	s_add_i32 m0, s30, 0x2000
	s_nop 0
	global_load_lds_dwordx4 v[212:213], off
	v_lshl_add_u64 v[212:213], v[234:235], 0, s[62:63]
	s_mov_b32 m0, s18
	s_nop 0
	global_load_lds_dwordx4 v[212:213], off
	v_lshl_add_u64 v[212:213], v[236:237], 0, s[62:63]
	s_mov_b32 m0, s19
	s_nop 0
	global_load_lds_dwordx4 v[212:213], off
	s_waitcnt vmcnt(8)
	s_waitcnt lgkmcnt(0)
	s_barrier
	s_setprio 1
	s_waitcnt lgkmcnt(0)
	v_mfma_f32_16x16x32_bf16 v[62:65], v[130:133], v[176:179], v[62:65]
	v_mfma_f32_16x16x32_bf16 v[62:65], v[134:137], v[180:183], v[62:65]
	v_mfma_f32_16x16x32_bf16 v[46:49], v[134:137], v[192:195], v[46:49]
	v_mfma_f32_16x16x32_bf16 v[46:49], v[130:133], v[188:191], v[46:49]
	v_mfma_f32_16x16x32_bf16 v[30:33], v[130:133], v[196:199], v[30:33]
	v_mfma_f32_16x16x32_bf16 v[30:33], v[134:137], v[200:203], v[30:33]
	v_mfma_f32_16x16x32_bf16 v[14:17], v[134:137], v[208:211], v[14:17]
	v_mfma_f32_16x16x32_bf16 v[14:17], v[130:133], v[204:207], v[14:17]
	v_mfma_f32_16x16x32_bf16 v[58:61], v[138:141], v[176:179], v[58:61]
	v_mfma_f32_16x16x32_bf16 v[58:61], v[142:145], v[180:183], v[58:61]
	v_mfma_f32_16x16x32_bf16 v[42:45], v[142:145], v[192:195], v[42:45]
	v_mfma_f32_16x16x32_bf16 v[42:45], v[138:141], v[188:191], v[42:45]
	v_mfma_f32_16x16x32_bf16 v[26:29], v[138:141], v[196:199], v[26:29]
	v_mfma_f32_16x16x32_bf16 v[26:29], v[142:145], v[200:203], v[26:29]
	v_mfma_f32_16x16x32_bf16 v[10:13], v[142:145], v[208:211], v[10:13]
	v_mfma_f32_16x16x32_bf16 v[10:13], v[138:141], v[204:207], v[10:13]
	s_setprio 0
	s_setprio 1
	v_mfma_f32_16x16x32_bf16 v[54:57], v[146:149], v[176:179], v[54:57]
	v_mfma_f32_16x16x32_bf16 v[54:57], v[150:153], v[180:183], v[54:57]
	v_mfma_f32_16x16x32_bf16 v[38:41], v[150:153], v[192:195], v[38:41]
	v_mfma_f32_16x16x32_bf16 v[38:41], v[146:149], v[188:191], v[38:41]
	v_mfma_f32_16x16x32_bf16 v[22:25], v[146:149], v[196:199], v[22:25]
	v_mfma_f32_16x16x32_bf16 v[22:25], v[150:153], v[200:203], v[22:25]
	v_mfma_f32_16x16x32_bf16 v[6:9], v[150:153], v[208:211], v[6:9]
	v_mfma_f32_16x16x32_bf16 v[6:9], v[146:149], v[204:207], v[6:9]
	v_mfma_f32_16x16x32_bf16 v[50:53], v[154:157], v[176:179], v[50:53]
	v_mfma_f32_16x16x32_bf16 v[50:53], v[172:175], v[180:183], v[50:53]
	v_mfma_f32_16x16x32_bf16 v[34:37], v[172:175], v[192:195], v[34:37]
	v_mfma_f32_16x16x32_bf16 v[34:37], v[154:157], v[188:191], v[34:37]
	v_mfma_f32_16x16x32_bf16 v[18:21], v[154:157], v[196:199], v[18:21]
	v_mfma_f32_16x16x32_bf16 v[18:21], v[172:175], v[200:203], v[18:21]
	v_mfma_f32_16x16x32_bf16 v[2:5], v[172:175], v[208:211], v[2:5]
	v_mfma_f32_16x16x32_bf16 v[2:5], v[154:157], v[204:207], v[2:5]
	s_setprio 0
	s_barrier
	s_add_i32 s27, s27, 2
	s_add_u32 s54, s54, 0x100
	s_addc_u32 s55, s55, 0
	s_add_u32 s25, s25, 0x100
	s_addc_u32 s26, s26, 0
	s_cmp_gt_u32 s27, 29
	s_cbranch_scc0 .LBB0_32
	s_and_b64 vcc, exec, s[2:3]
	s_cbranch_vccz .LBB0_35
	s_barrier

.LBB0_132:
	s_add_u32 s23, s48, 0xfff80080
	s_addc_u32 s24, s49, -1
	s_add_i32 s25, 0, 0x10000
	s_cmp_eq_u32 s22, 28
	s_cselect_b32 s69, s3, s24
	s_cselect_b32 s68, s18, s23
	s_cselect_b32 s51, s1, s21
	s_cselect_b32 s50, s19, s20
	s_add_i32 s23, 0, 0x14000
	v_add_u32_e32 v156, s25, v165
	v_add_u32_e32 v169, s23, v165
	ds_read_b128 v[144:147], v156
	ds_read_b128 v[148:151], v156 offset:1024
	ds_read_b128 v[152:155], v156 offset:2048
	ds_read_b128 v[156:159], v156 offset:3072
	ds_read_b128 v[160:163], v169
	ds_read_b128 v[170:173], v169 offset:1024
	ds_read_b128 v[174:177], v169 offset:2048
	ds_read_b128 v[178:181], v169 offset:3072
	v_lshl_add_u64 v[232:233], s[48:49], 0, v[140:141]
	s_add_i32 m0, s45, 0xc000
	ds_read_b128 v[182:185], v168
	ds_read_b128 v[186:189], v168 offset:1024
	ds_read_b128 v[190:193], v168 offset:2048
	ds_read_b128 v[194:197], v168 offset:3072
	ds_read_b128 v[198:201], v168 offset:4096
	ds_read_b128 v[202:205], v168 offset:5120
	ds_read_b128 v[206:209], v168 offset:6144
	ds_read_b128 v[210:213], v168 offset:7168
	global_load_lds_dwordx4 v[232:233], off
	v_lshl_add_u64 v[232:233], s[48:49], 0, v[142:143]
	s_add_i32 m0, s45, 0xe000
	s_nop 0
	global_load_lds_dwordx4 v[232:233], off
	s_waitcnt vmcnt(8)
	s_waitcnt lgkmcnt(0)
	s_barrier
	s_setprio 1
	s_waitcnt lgkmcnt(0)
	v_mfma_f32_16x16x32_bf16 v[126:129], v[144:147], v[182:185], v[126:129]
	v_mfma_f32_16x16x32_bf16 v[126:129], v[148:151], v[186:189], v[126:129]
	v_mfma_f32_16x16x32_bf16 v[110:113], v[148:151], v[194:197], v[110:113]
	v_mfma_f32_16x16x32_bf16 v[110:113], v[144:147], v[190:193], v[110:113]
	v_mfma_f32_16x16x32_bf16 v[102:105], v[144:147], v[198:201], v[102:105]
	v_mfma_f32_16x16x32_bf16 v[102:105], v[148:151], v[202:205], v[102:105]
	v_mfma_f32_16x16x32_bf16 v[86:89], v[148:151], v[210:213], v[86:89]
	v_mfma_f32_16x16x32_bf16 v[86:89], v[144:147], v[206:209], v[86:89]
	v_mfma_f32_16x16x32_bf16 v[122:125], v[152:155], v[182:185], v[122:125]
	v_mfma_f32_16x16x32_bf16 v[122:125], v[156:159], v[186:189], v[122:125]
	v_mfma_f32_16x16x32_bf16 v[106:109], v[156:159], v[194:197], v[106:109]
	v_mfma_f32_16x16x32_bf16 v[106:109], v[152:155], v[190:193], v[106:109]
	v_mfma_f32_16x16x32_bf16 v[94:97], v[152:155], v[198:201], v[94:97]
	v_mfma_f32_16x16x32_bf16 v[94:97], v[156:159], v[202:205], v[94:97]
	v_mfma_f32_16x16x32_bf16 v[78:81], v[156:159], v[210:213], v[78:81]
	v_mfma_f32_16x16x32_bf16 v[78:81], v[152:155], v[206:209], v[78:81]
	s_setprio 0
	s_setprio 1
	v_mfma_f32_16x16x32_bf16 v[118:121], v[160:163], v[182:185], v[118:121]
	v_mfma_f32_16x16x32_bf16 v[118:121], v[170:173], v[186:189], v[118:121]
	v_mfma_f32_16x16x32_bf16 v[98:101], v[170:173], v[194:197], v[98:101]
	v_mfma_f32_16x16x32_bf16 v[98:101], v[160:163], v[190:193], v[98:101]
	v_mfma_f32_16x16x32_bf16 v[82:85], v[160:163], v[198:201], v[82:85]
	v_mfma_f32_16x16x32_bf16 v[82:85], v[170:173], v[202:205], v[82:85]
	v_mfma_f32_16x16x32_bf16 v[70:73], v[170:173], v[210:213], v[70:73]
	v_mfma_f32_16x16x32_bf16 v[70:73], v[160:163], v[206:209], v[70:73]
	v_mfma_f32_16x16x32_bf16 v[114:117], v[174:177], v[182:185], v[114:117]
	v_mfma_f32_16x16x32_bf16 v[114:117], v[178:181], v[186:189], v[114:117]
	v_mfma_f32_16x16x32_bf16 v[90:93], v[178:181], v[194:197], v[90:93]
	v_mfma_f32_16x16x32_bf16 v[90:93], v[174:177], v[190:193], v[90:93]
	v_mfma_f32_16x16x32_bf16 v[74:77], v[174:177], v[198:201], v[74:77]
	v_mfma_f32_16x16x32_bf16 v[74:77], v[178:181], v[202:205], v[74:77]
	v_mfma_f32_16x16x32_bf16 v[66:69], v[178:181], v[210:213], v[66:69]
	v_mfma_f32_16x16x32_bf16 v[66:69], v[174:177], v[206:209], v[66:69]
	s_setprio 0
	s_barrier
	s_add_i32 s24, s25, s16
	v_lshl_add_u64 v[232:233], s[50:51], 0, v[132:133]
	s_mov_b32 m0, s24
	ds_read_b128 v[182:185], v168 offset:16384
	ds_read_b128 v[186:189], v168 offset:17408
	ds_read_b128 v[190:193], v168 offset:18432
	ds_read_b128 v[194:197], v168 offset:19456
	ds_read_b128 v[198:201], v168 offset:20480
	ds_read_b128 v[202:205], v168 offset:21504
	ds_read_b128 v[206:209], v168 offset:22528
	ds_read_b128 v[210:213], v168 offset:23552
	global_load_lds_dwordx4 v[232:233], off
	s_add_i32 m0, s24, 0x2000
	s_add_u32 s24, s50, 0x80000
	v_lshl_add_u64 v[234:235], s[50:51], 0, v[136:137]
	s_addc_u32 s25, s51, 0
	s_add_i32 s23, s23, s16
	global_load_lds_dwordx4 v[234:235], off
	v_lshl_add_u64 v[236:237], s[24:25], 0, v[132:133]
	s_mov_b32 m0, s23
	v_lshl_add_u64 v[238:239], s[68:69], 0, v[134:135]
	global_load_lds_dwordx4 v[236:237], off
	v_lshl_add_u64 v[236:237], s[24:25], 0, v[136:137]
	s_add_i32 m0, s23, 0x2000
	s_nop 0
	global_load_lds_dwordx4 v[236:237], off
	v_lshl_add_u64 v[236:237], s[68:69], 0, v[130:131]
	s_mov_b32 m0, s45
	s_nop 0
	global_load_lds_dwordx4 v[236:237], off
	s_mov_b32 m0, s57
	s_nop 0
	global_load_lds_dwordx4 v[238:239], off
	s_waitcnt vmcnt(8)
	s_waitcnt lgkmcnt(0)
	s_barrier
	s_setprio 1
	s_waitcnt lgkmcnt(0)
	v_mfma_f32_16x16x32_bf16 v[62:65], v[144:147], v[182:185], v[62:65]
	v_mfma_f32_16x16x32_bf16 v[62:65], v[148:151], v[186:189], v[62:65]
	v_mfma_f32_16x16x32_bf16 v[54:57], v[148:151], v[194:197], v[54:57]
	v_mfma_f32_16x16x32_bf16 v[54:57], v[144:147], v[190:193], v[54:57]
	v_mfma_f32_16x16x32_bf16 v[38:41], v[144:147], v[198:201], v[38:41]
	v_mfma_f32_16x16x32_bf16 v[38:41], v[148:151], v[202:205], v[38:41]
	v_mfma_f32_16x16x32_bf16 v[22:25], v[148:151], v[210:213], v[22:25]
	v_mfma_f32_16x16x32_bf16 v[22:25], v[144:147], v[206:209], v[22:25]
	v_mfma_f32_16x16x32_bf16 v[58:61], v[152:155], v[182:185], v[58:61]
	v_mfma_f32_16x16x32_bf16 v[58:61], v[156:159], v[186:189], v[58:61]
	v_mfma_f32_16x16x32_bf16 v[46:49], v[156:159], v[194:197], v[46:49]
	v_mfma_f32_16x16x32_bf16 v[46:49], v[152:155], v[190:193], v[46:49]
	v_mfma_f32_16x16x32_bf16 v[30:33], v[152:155], v[198:201], v[30:33]
	v_mfma_f32_16x16x32_bf16 v[30:33], v[156:159], v[202:205], v[30:33]
	v_mfma_f32_16x16x32_bf16 v[14:17], v[156:159], v[210:213], v[14:17]
	v_mfma_f32_16x16x32_bf16 v[14:17], v[152:155], v[206:209], v[14:17]
	s_setprio 0
	s_setprio 1
	v_mfma_f32_16x16x32_bf16 v[50:53], v[160:163], v[182:185], v[50:53]
	v_mfma_f32_16x16x32_bf16 v[50:53], v[170:173], v[186:189], v[50:53]
	v_mfma_f32_16x16x32_bf16 v[34:37], v[170:173], v[194:197], v[34:37]
	v_mfma_f32_16x16x32_bf16 v[34:37], v[160:163], v[190:193], v[34:37]
	v_mfma_f32_16x16x32_bf16 v[18:21], v[160:163], v[198:201], v[18:21]
	v_mfma_f32_16x16x32_bf16 v[18:21], v[170:173], v[202:205], v[18:21]
	v_mfma_f32_16x16x32_bf16 v[6:9], v[170:173], v[210:213], v[6:9]
	v_mfma_f32_16x16x32_bf16 v[6:9], v[160:163], v[206:209], v[6:9]
	v_mfma_f32_16x16x32_bf16 v[42:45], v[174:177], v[182:185], v[42:45]
	v_mfma_f32_16x16x32_bf16 v[42:45], v[178:181], v[186:189], v[42:45]
	v_mfma_f32_16x16x32_bf16 v[26:29], v[178:181], v[194:197], v[26:29]
	v_mfma_f32_16x16x32_bf16 v[26:29], v[174:177], v[190:193], v[26:29]
	v_mfma_f32_16x16x32_bf16 v[10:13], v[174:177], v[198:201], v[10:13]
	v_mfma_f32_16x16x32_bf16 v[10:13], v[178:181], v[202:205], v[10:13]
	v_mfma_f32_16x16x32_bf16 v[2:5], v[178:181], v[210:213], v[2:5]
	v_mfma_f32_16x16x32_bf16 v[2:5], v[174:177], v[206:209], v[2:5]
	s_setprio 0
	s_barrier
	s_add_i32 s23, 0, 0x18000
	s_add_i32 s26, 0, 0x1c000
	v_add_u32_e32 v156, s23, v165
	v_add_u32_e32 v169, s26, v165
	ds_read_b128 v[144:147], v156
	ds_read_b128 v[148:151], v156 offset:1024
	ds_read_b128 v[152:155], v156 offset:2048
	ds_read_b128 v[156:159], v156 offset:3072
	ds_read_b128 v[160:163], v169
	ds_read_b128 v[170:173], v169 offset:1024
	ds_read_b128 v[174:177], v169 offset:2048
	ds_read_b128 v[178:181], v169 offset:3072
	s_add_u32 s24, s68, 0x80000
	s_addc_u32 s25, s69, 0
	s_mov_b32 m0, s42
	v_lshl_add_u64 v[240:241], s[24:25], 0, v[130:131]
	ds_read_b128 v[182:185], v168 offset:32768
	ds_read_b128 v[186:189], v168 offset:33792
	ds_read_b128 v[190:193], v168 offset:34816
	ds_read_b128 v[194:197], v168 offset:35840
	ds_read_b128 v[198:201], v168 offset:36864
	ds_read_b128 v[202:205], v168 offset:37888
	ds_read_b128 v[206:209], v168 offset:38912
	ds_read_b128 v[210:213], v168 offset:39936
	global_load_lds_dwordx4 v[240:241], off
	v_lshl_add_u64 v[240:241], s[24:25], 0, v[134:135]
	s_mov_b32 m0, s6
	s_nop 0
	global_load_lds_dwordx4 v[240:241], off
	s_waitcnt vmcnt(8)
	s_waitcnt lgkmcnt(0)
	s_barrier
	s_setprio 1
	s_waitcnt lgkmcnt(0)
	v_mfma_f32_16x16x32_bf16 v[126:129], v[144:147], v[182:185], v[126:129]
	v_mfma_f32_16x16x32_bf16 v[126:129], v[148:151], v[186:189], v[126:129]
	v_mfma_f32_16x16x32_bf16 v[110:113], v[148:151], v[194:197], v[110:113]
	v_mfma_f32_16x16x32_bf16 v[110:113], v[144:147], v[190:193], v[110:113]
	v_mfma_f32_16x16x32_bf16 v[102:105], v[144:147], v[198:201], v[102:105]
	v_mfma_f32_16x16x32_bf16 v[102:105], v[148:151], v[202:205], v[102:105]
	v_mfma_f32_16x16x32_bf16 v[86:89], v[148:151], v[210:213], v[86:89]
	v_mfma_f32_16x16x32_bf16 v[86:89], v[144:147], v[206:209], v[86:89]
	v_mfma_f32_16x16x32_bf16 v[122:125], v[152:155], v[182:185], v[122:125]
	v_mfma_f32_16x16x32_bf16 v[122:125], v[156:159], v[186:189], v[122:125]
	v_mfma_f32_16x16x32_bf16 v[106:109], v[156:159], v[194:197], v[106:109]
	v_mfma_f32_16x16x32_bf16 v[106:109], v[152:155], v[190:193], v[106:109]
	v_mfma_f32_16x16x32_bf16 v[94:97], v[152:155], v[198:201], v[94:97]
	v_mfma_f32_16x16x32_bf16 v[94:97], v[156:159], v[202:205], v[94:97]
	v_mfma_f32_16x16x32_bf16 v[78:81], v[156:159], v[210:213], v[78:81]
	v_mfma_f32_16x16x32_bf16 v[78:81], v[152:155], v[206:209], v[78:81]
	s_setprio 0
	s_setprio 1
	v_mfma_f32_16x16x32_bf16 v[118:121], v[160:163], v[182:185], v[118:121]
	v_mfma_f32_16x16x32_bf16 v[118:121], v[170:173], v[186:189], v[118:121]
	v_mfma_f32_16x16x32_bf16 v[98:101], v[170:173], v[194:197], v[98:101]
	v_mfma_f32_16x16x32_bf16 v[98:101], v[160:163], v[190:193], v[98:101]
	v_mfma_f32_16x16x32_bf16 v[82:85], v[160:163], v[198:201], v[82:85]
	v_mfma_f32_16x16x32_bf16 v[82:85], v[170:173], v[202:205], v[82:85]
	v_mfma_f32_16x16x32_bf16 v[70:73], v[170:173], v[210:213], v[70:73]
	v_mfma_f32_16x16x32_bf16 v[70:73], v[160:163], v[206:209], v[70:73]
	v_mfma_f32_16x16x32_bf16 v[114:117], v[174:177], v[182:185], v[114:117]
	v_mfma_f32_16x16x32_bf16 v[114:117], v[178:181], v[186:189], v[114:117]
	v_mfma_f32_16x16x32_bf16 v[90:93], v[178:181], v[194:197], v[90:93]
	v_mfma_f32_16x16x32_bf16 v[90:93], v[174:177], v[190:193], v[90:93]
	v_mfma_f32_16x16x32_bf16 v[74:77], v[174:177], v[198:201], v[74:77]
	v_mfma_f32_16x16x32_bf16 v[74:77], v[178:181], v[202:205], v[74:77]
	v_mfma_f32_16x16x32_bf16 v[66:69], v[178:181], v[210:213], v[66:69]
	v_mfma_f32_16x16x32_bf16 v[66:69], v[174:177], v[206:209], v[66:69]
	s_setprio 0
	s_barrier
	s_add_i32 s23, s23, s16
	v_lshl_add_u64 v[232:233], v[232:233], 0, s[62:63]
	s_mov_b32 m0, s23
	ds_read_b128 v[182:185], v168 offset:49152
	ds_read_b128 v[186:189], v168 offset:50176
	ds_read_b128 v[190:193], v168 offset:51200
	ds_read_b128 v[194:197], v168 offset:52224
	ds_read_b128 v[198:201], v168 offset:53248
	ds_read_b128 v[202:205], v168 offset:54272
	ds_read_b128 v[206:209], v168 offset:55296
	ds_read_b128 v[210:213], v168 offset:56320
	global_load_lds_dwordx4 v[232:233], off
	s_add_i32 m0, s23, 0x2000
	s_add_u32 s24, s50, 0x80080
	v_lshl_add_u64 v[232:233], v[234:235], 0, s[62:63]
	s_addc_u32 s25, s51, 0
	s_add_i32 s23, s26, s16
	global_load_lds_dwordx4 v[232:233], off
	v_lshl_add_u64 v[232:233], s[24:25], 0, v[132:133]
	s_mov_b32 m0, s23
	s_nop 0
	global_load_lds_dwordx4 v[232:233], off
	v_lshl_add_u64 v[232:233], s[24:25], 0, v[136:137]
	s_add_i32 m0, s23, 0x2000
	s_nop 0
	global_load_lds_dwordx4 v[232:233], off
	v_lshl_add_u64 v[232:233], v[236:237], 0, s[62:63]
	s_mov_b32 m0, s76
	s_nop 0
	global_load_lds_dwordx4 v[232:233], off
	v_lshl_add_u64 v[232:233], v[238:239], 0, s[62:63]
	s_mov_b32 m0, s77
	s_nop 0
	global_load_lds_dwordx4 v[232:233], off
	s_waitcnt vmcnt(8)
	s_waitcnt lgkmcnt(0)
	s_barrier
	s_setprio 1
	s_waitcnt lgkmcnt(0)
	v_mfma_f32_16x16x32_bf16 v[62:65], v[144:147], v[182:185], v[62:65]
	v_mfma_f32_16x16x32_bf16 v[62:65], v[148:151], v[186:189], v[62:65]
	v_mfma_f32_16x16x32_bf16 v[54:57], v[148:151], v[194:197], v[54:57]
	v_mfma_f32_16x16x32_bf16 v[54:57], v[144:147], v[190:193], v[54:57]
	v_mfma_f32_16x16x32_bf16 v[38:41], v[144:147], v[198:201], v[38:41]
	v_mfma_f32_16x16x32_bf16 v[38:41], v[148:151], v[202:205], v[38:41]
	v_mfma_f32_16x16x32_bf16 v[22:25], v[148:151], v[210:213], v[22:25]
	v_mfma_f32_16x16x32_bf16 v[22:25], v[144:147], v[206:209], v[22:25]
	v_mfma_f32_16x16x32_bf16 v[58:61], v[152:155], v[182:185], v[58:61]
	v_mfma_f32_16x16x32_bf16 v[58:61], v[156:159], v[186:189], v[58:61]
	v_mfma_f32_16x16x32_bf16 v[46:49], v[156:159], v[194:197], v[46:49]
	v_mfma_f32_16x16x32_bf16 v[46:49], v[152:155], v[190:193], v[46:49]
	v_mfma_f32_16x16x32_bf16 v[30:33], v[152:155], v[198:201], v[30:33]
	v_mfma_f32_16x16x32_bf16 v[30:33], v[156:159], v[202:205], v[30:33]
	v_mfma_f32_16x16x32_bf16 v[14:17], v[156:159], v[210:213], v[14:17]
	v_mfma_f32_16x16x32_bf16 v[14:17], v[152:155], v[206:209], v[14:17]
	s_setprio 0
	s_setprio 1
	v_mfma_f32_16x16x32_bf16 v[50:53], v[160:163], v[182:185], v[50:53]
	v_mfma_f32_16x16x32_bf16 v[50:53], v[170:173], v[186:189], v[50:53]
	v_mfma_f32_16x16x32_bf16 v[34:37], v[170:173], v[194:197], v[34:37]
	v_mfma_f32_16x16x32_bf16 v[34:37], v[160:163], v[190:193], v[34:37]
	v_mfma_f32_16x16x32_bf16 v[18:21], v[160:163], v[198:201], v[18:21]
	v_mfma_f32_16x16x32_bf16 v[18:21], v[170:173], v[202:205], v[18:21]
	v_mfma_f32_16x16x32_bf16 v[6:9], v[170:173], v[210:213], v[6:9]
	v_mfma_f32_16x16x32_bf16 v[6:9], v[160:163], v[206:209], v[6:9]
	v_mfma_f32_16x16x32_bf16 v[42:45], v[174:177], v[182:185], v[42:45]
	v_mfma_f32_16x16x32_bf16 v[42:45], v[178:181], v[186:189], v[42:45]
	v_mfma_f32_16x16x32_bf16 v[26:29], v[178:181], v[194:197], v[26:29]
	v_mfma_f32_16x16x32_bf16 v[26:29], v[174:177], v[190:193], v[26:29]
	v_mfma_f32_16x16x32_bf16 v[10:13], v[174:177], v[198:201], v[10:13]
	v_mfma_f32_16x16x32_bf16 v[10:13], v[178:181], v[202:205], v[10:13]
	v_mfma_f32_16x16x32_bf16 v[2:5], v[178:181], v[210:213], v[2:5]
	v_mfma_f32_16x16x32_bf16 v[2:5], v[174:177], v[206:209], v[2:5]
	s_setprio 0
	s_barrier
	s_add_i32 s22, s22, 2
	s_add_u32 s48, s48, 0x100
	s_addc_u32 s49, s49, 0
	s_add_u32 s20, s20, 0x100
	s_addc_u32 s21, s21, 0
	s_cmp_gt_u32 s22, 29
	s_cbranch_scc0 .LBB0_132
	s_and_b64 vcc, exec, s[10:11]
	s_cbranch_vccz .LBB0_135
	s_barrier

.LBB0_238:
	s_add_u32 s10, s12, 0x100
	s_addc_u32 s11, s13, 0
	s_add_i32 s23, 0, 0x10000
	s_cmpk_eq_i32 s22, 0x52
	s_cselect_b32 vcc_hi, s47, s11
	s_cselect_b32 vcc_lo, s46, s10
	s_cselect_b32 s51, s49, s21
	s_cselect_b32 s50, s48, s20
	s_add_i32 s24, 0, 0x14000
	v_add_u32_e32 v142, s23, v194
	v_add_u32_e32 v158, s24, v194
	ds_read_b128 v[122:125], v142
	ds_read_b128 v[126:129], v142 offset:1024
	ds_read_b128 v[138:141], v142 offset:2048
	ds_read_b128 v[142:145], v142 offset:3072
	ds_read_b128 v[146:149], v158
	ds_read_b128 v[150:153], v158 offset:1024
	ds_read_b128 v[154:157], v158 offset:2048
	ds_read_b128 v[158:161], v158 offset:3072
	v_lshl_add_u64 v[212:213], s[12:13], 0, v[170:171]
	s_add_i32 m0, s57, 0xc000
	ds_read_b128 v[174:177], v198
	ds_read_b128 v[178:181], v198 offset:1024
	ds_read_b128 v[182:185], v198 offset:2048
	ds_read_b128 v[186:189], v198 offset:3072
	ds_read_b128 v[190:193], v198 offset:4096
	ds_read_b128 v[200:203], v198 offset:5120
	ds_read_b128 v[204:207], v198 offset:6144
	ds_read_b128 v[208:211], v198 offset:7168
	global_load_lds_dwordx4 v[212:213], off
	v_lshl_add_u64 v[212:213], s[12:13], 0, v[172:173]
	s_add_i32 m0, s57, 0xe000
	s_nop 0
	global_load_lds_dwordx4 v[212:213], off
	s_waitcnt vmcnt(8)
	s_waitcnt lgkmcnt(0)
	s_barrier
	s_setprio 1
	s_waitcnt lgkmcnt(0)
	v_mfma_f32_16x16x32_bf16 v[134:137], v[122:125], v[174:177], v[134:137]
	v_mfma_f32_16x16x32_bf16 v[134:137], v[126:129], v[178:181], v[134:137]
	v_mfma_f32_16x16x32_bf16 v[110:113], v[126:129], v[186:189], v[110:113]
	v_mfma_f32_16x16x32_bf16 v[110:113], v[122:125], v[182:185], v[110:113]
	v_mfma_f32_16x16x32_bf16 v[94:97], v[122:125], v[190:193], v[94:97]
	v_mfma_f32_16x16x32_bf16 v[94:97], v[126:129], v[200:203], v[94:97]
	v_mfma_f32_16x16x32_bf16 v[78:81], v[126:129], v[208:211], v[78:81]
	v_mfma_f32_16x16x32_bf16 v[78:81], v[122:125], v[204:207], v[78:81]
	v_mfma_f32_16x16x32_bf16 v[130:133], v[138:141], v[174:177], v[130:133]
	v_mfma_f32_16x16x32_bf16 v[130:133], v[142:145], v[178:181], v[130:133]
	v_mfma_f32_16x16x32_bf16 v[106:109], v[142:145], v[186:189], v[106:109]
	v_mfma_f32_16x16x32_bf16 v[106:109], v[138:141], v[182:185], v[106:109]
	v_mfma_f32_16x16x32_bf16 v[90:93], v[138:141], v[190:193], v[90:93]
	v_mfma_f32_16x16x32_bf16 v[90:93], v[142:145], v[200:203], v[90:93]
	v_mfma_f32_16x16x32_bf16 v[74:77], v[142:145], v[208:211], v[74:77]
	v_mfma_f32_16x16x32_bf16 v[74:77], v[138:141], v[204:207], v[74:77]
	s_setprio 0
	s_setprio 1
	v_mfma_f32_16x16x32_bf16 v[118:121], v[146:149], v[174:177], v[118:121]
	v_mfma_f32_16x16x32_bf16 v[118:121], v[150:153], v[178:181], v[118:121]
	v_mfma_f32_16x16x32_bf16 v[102:105], v[150:153], v[186:189], v[102:105]
	v_mfma_f32_16x16x32_bf16 v[102:105], v[146:149], v[182:185], v[102:105]
	v_mfma_f32_16x16x32_bf16 v[86:89], v[146:149], v[190:193], v[86:89]
	v_mfma_f32_16x16x32_bf16 v[86:89], v[150:153], v[200:203], v[86:89]
	v_mfma_f32_16x16x32_bf16 v[70:73], v[150:153], v[208:211], v[70:73]
	v_mfma_f32_16x16x32_bf16 v[70:73], v[146:149], v[204:207], v[70:73]
	v_mfma_f32_16x16x32_bf16 v[114:117], v[154:157], v[174:177], v[114:117]
	v_mfma_f32_16x16x32_bf16 v[114:117], v[158:161], v[178:181], v[114:117]
	v_mfma_f32_16x16x32_bf16 v[98:101], v[158:161], v[186:189], v[98:101]
	v_mfma_f32_16x16x32_bf16 v[98:101], v[154:157], v[182:185], v[98:101]
	v_mfma_f32_16x16x32_bf16 v[82:85], v[154:157], v[190:193], v[82:85]
	v_mfma_f32_16x16x32_bf16 v[82:85], v[158:161], v[200:203], v[82:85]
	v_mfma_f32_16x16x32_bf16 v[66:69], v[158:161], v[208:211], v[66:69]
	v_mfma_f32_16x16x32_bf16 v[66:69], v[154:157], v[204:207], v[66:69]
	s_setprio 0
	s_barrier
	s_add_i32 s12, s23, s42
	v_lshl_add_u64 v[212:213], s[50:51], 0, v[164:165]
	s_mov_b32 m0, s12
	ds_read_b128 v[174:177], v198 offset:16384
	ds_read_b128 v[178:181], v198 offset:17408
	ds_read_b128 v[182:185], v198 offset:18432
	ds_read_b128 v[186:189], v198 offset:19456
	ds_read_b128 v[190:193], v198 offset:20480
	ds_read_b128 v[200:203], v198 offset:21504
	ds_read_b128 v[204:207], v198 offset:22528
	ds_read_b128 v[208:211], v198 offset:23552
	global_load_lds_dwordx4 v[212:213], off
	s_add_i32 m0, s12, 0x2000
	s_add_u32 s12, s50, 0x158000
	v_lshl_add_u64 v[232:233], s[50:51], 0, v[168:169]
	s_addc_u32 s13, s51, 0
	s_add_i32 s23, s24, s42
	global_load_lds_dwordx4 v[232:233], off
	v_lshl_add_u64 v[234:235], s[12:13], 0, v[164:165]
	s_mov_b32 m0, s23
	v_lshl_add_u64 v[236:237], vcc, 0, v[166:167]
	global_load_lds_dwordx4 v[234:235], off
	v_lshl_add_u64 v[234:235], s[12:13], 0, v[168:169]
	s_add_i32 m0, s23, 0x2000
	s_nop 0
	global_load_lds_dwordx4 v[234:235], off
	v_lshl_add_u64 v[234:235], vcc, 0, v[162:163]
	s_mov_b32 m0, s57
	s_nop 0
	global_load_lds_dwordx4 v[234:235], off
	s_mov_b32 m0, s58
	s_nop 0
	global_load_lds_dwordx4 v[236:237], off
	s_waitcnt vmcnt(8)
	s_waitcnt lgkmcnt(0)
	s_barrier
	s_setprio 1
	s_waitcnt lgkmcnt(0)
	v_mfma_f32_16x16x32_bf16 v[62:65], v[122:125], v[174:177], v[62:65]
	v_mfma_f32_16x16x32_bf16 v[62:65], v[126:129], v[178:181], v[62:65]
	v_mfma_f32_16x16x32_bf16 v[46:49], v[126:129], v[186:189], v[46:49]
	v_mfma_f32_16x16x32_bf16 v[46:49], v[122:125], v[182:185], v[46:49]
	v_mfma_f32_16x16x32_bf16 v[30:33], v[122:125], v[190:193], v[30:33]
	v_mfma_f32_16x16x32_bf16 v[30:33], v[126:129], v[200:203], v[30:33]
	v_mfma_f32_16x16x32_bf16 v[14:17], v[126:129], v[208:211], v[14:17]
	v_mfma_f32_16x16x32_bf16 v[14:17], v[122:125], v[204:207], v[14:17]
	v_mfma_f32_16x16x32_bf16 v[58:61], v[138:141], v[174:177], v[58:61]
	v_mfma_f32_16x16x32_bf16 v[58:61], v[142:145], v[178:181], v[58:61]
	v_mfma_f32_16x16x32_bf16 v[42:45], v[142:145], v[186:189], v[42:45]
	v_mfma_f32_16x16x32_bf16 v[42:45], v[138:141], v[182:185], v[42:45]
	v_mfma_f32_16x16x32_bf16 v[26:29], v[138:141], v[190:193], v[26:29]
	v_mfma_f32_16x16x32_bf16 v[26:29], v[142:145], v[200:203], v[26:29]
	v_mfma_f32_16x16x32_bf16 v[10:13], v[142:145], v[208:211], v[10:13]
	v_mfma_f32_16x16x32_bf16 v[10:13], v[138:141], v[204:207], v[10:13]
	s_setprio 0
	s_setprio 1
	v_mfma_f32_16x16x32_bf16 v[54:57], v[146:149], v[174:177], v[54:57]
	v_mfma_f32_16x16x32_bf16 v[54:57], v[150:153], v[178:181], v[54:57]
	v_mfma_f32_16x16x32_bf16 v[38:41], v[150:153], v[186:189], v[38:41]
	v_mfma_f32_16x16x32_bf16 v[38:41], v[146:149], v[182:185], v[38:41]
	v_mfma_f32_16x16x32_bf16 v[22:25], v[146:149], v[190:193], v[22:25]
	v_mfma_f32_16x16x32_bf16 v[22:25], v[150:153], v[200:203], v[22:25]
	v_mfma_f32_16x16x32_bf16 v[6:9], v[150:153], v[208:211], v[6:9]
	v_mfma_f32_16x16x32_bf16 v[6:9], v[146:149], v[204:207], v[6:9]
	v_mfma_f32_16x16x32_bf16 v[50:53], v[154:157], v[174:177], v[50:53]
	v_mfma_f32_16x16x32_bf16 v[50:53], v[158:161], v[178:181], v[50:53]
	v_mfma_f32_16x16x32_bf16 v[34:37], v[158:161], v[186:189], v[34:37]
	v_mfma_f32_16x16x32_bf16 v[34:37], v[154:157], v[182:185], v[34:37]
	v_mfma_f32_16x16x32_bf16 v[18:21], v[154:157], v[190:193], v[18:21]
	v_mfma_f32_16x16x32_bf16 v[18:21], v[158:161], v[200:203], v[18:21]
	v_mfma_f32_16x16x32_bf16 v[2:5], v[158:161], v[208:211], v[2:5]
	v_mfma_f32_16x16x32_bf16 v[2:5], v[154:157], v[204:207], v[2:5]
	s_setprio 0
	s_barrier
	s_add_i32 s23, 0, 0x18000
	s_add_i32 s24, 0, 0x1c000
	v_add_u32_e32 v142, s23, v194
	v_add_u32_e32 v158, s24, v194
	ds_read_b128 v[122:125], v142
	ds_read_b128 v[126:129], v142 offset:1024
	ds_read_b128 v[138:141], v142 offset:2048
	ds_read_b128 v[142:145], v142 offset:3072
	ds_read_b128 v[146:149], v158
	ds_read_b128 v[150:153], v158 offset:1024
	ds_read_b128 v[154:157], v158 offset:2048
	ds_read_b128 v[158:161], v158 offset:3072
	s_add_u32 s12, vcc_lo, 0x158000
	s_addc_u32 s13, vcc_hi, 0
	s_mov_b32 m0, s67
	v_lshl_add_u64 v[238:239], s[12:13], 0, v[162:163]
	ds_read_b128 v[174:177], v198 offset:32768
	ds_read_b128 v[178:181], v198 offset:33792
	ds_read_b128 v[182:185], v198 offset:34816
	ds_read_b128 v[186:189], v198 offset:35840
	ds_read_b128 v[190:193], v198 offset:36864
	ds_read_b128 v[200:203], v198 offset:37888
	ds_read_b128 v[204:207], v198 offset:38912
	ds_read_b128 v[208:211], v198 offset:39936
	global_load_lds_dwordx4 v[238:239], off
	v_lshl_add_u64 v[238:239], s[12:13], 0, v[166:167]
	s_mov_b32 m0, s76
	s_nop 0
	global_load_lds_dwordx4 v[238:239], off
	s_waitcnt vmcnt(8)
	s_waitcnt lgkmcnt(0)
	s_barrier
	s_setprio 1
	s_waitcnt lgkmcnt(0)
	v_mfma_f32_16x16x32_bf16 v[134:137], v[122:125], v[174:177], v[134:137]
	v_mfma_f32_16x16x32_bf16 v[134:137], v[126:129], v[178:181], v[134:137]
	v_mfma_f32_16x16x32_bf16 v[110:113], v[126:129], v[186:189], v[110:113]
	v_mfma_f32_16x16x32_bf16 v[110:113], v[122:125], v[182:185], v[110:113]
	v_mfma_f32_16x16x32_bf16 v[94:97], v[122:125], v[190:193], v[94:97]
	v_mfma_f32_16x16x32_bf16 v[94:97], v[126:129], v[200:203], v[94:97]
	v_mfma_f32_16x16x32_bf16 v[78:81], v[126:129], v[208:211], v[78:81]
	v_mfma_f32_16x16x32_bf16 v[78:81], v[122:125], v[204:207], v[78:81]
	v_mfma_f32_16x16x32_bf16 v[130:133], v[138:141], v[174:177], v[130:133]
	v_mfma_f32_16x16x32_bf16 v[130:133], v[142:145], v[178:181], v[130:133]
	v_mfma_f32_16x16x32_bf16 v[106:109], v[142:145], v[186:189], v[106:109]
	v_mfma_f32_16x16x32_bf16 v[106:109], v[138:141], v[182:185], v[106:109]
	v_mfma_f32_16x16x32_bf16 v[90:93], v[138:141], v[190:193], v[90:93]
	v_mfma_f32_16x16x32_bf16 v[90:93], v[142:145], v[200:203], v[90:93]
	v_mfma_f32_16x16x32_bf16 v[74:77], v[142:145], v[208:211], v[74:77]
	v_mfma_f32_16x16x32_bf16 v[74:77], v[138:141], v[204:207], v[74:77]
	s_setprio 0
	s_setprio 1
	v_mfma_f32_16x16x32_bf16 v[118:121], v[146:149], v[174:177], v[118:121]
	v_mfma_f32_16x16x32_bf16 v[118:121], v[150:153], v[178:181], v[118:121]
	v_mfma_f32_16x16x32_bf16 v[102:105], v[150:153], v[186:189], v[102:105]
	v_mfma_f32_16x16x32_bf16 v[102:105], v[146:149], v[182:185], v[102:105]
	v_mfma_f32_16x16x32_bf16 v[86:89], v[146:149], v[190:193], v[86:89]
	v_mfma_f32_16x16x32_bf16 v[86:89], v[150:153], v[200:203], v[86:89]
	v_mfma_f32_16x16x32_bf16 v[70:73], v[150:153], v[208:211], v[70:73]
	v_mfma_f32_16x16x32_bf16 v[70:73], v[146:149], v[204:207], v[70:73]
	v_mfma_f32_16x16x32_bf16 v[114:117], v[154:157], v[174:177], v[114:117]
	v_mfma_f32_16x16x32_bf16 v[114:117], v[158:161], v[178:181], v[114:117]
	v_mfma_f32_16x16x32_bf16 v[98:101], v[158:161], v[186:189], v[98:101]
	v_mfma_f32_16x16x32_bf16 v[98:101], v[154:157], v[182:185], v[98:101]
	v_mfma_f32_16x16x32_bf16 v[82:85], v[154:157], v[190:193], v[82:85]
	v_mfma_f32_16x16x32_bf16 v[82:85], v[158:161], v[200:203], v[82:85]
	v_mfma_f32_16x16x32_bf16 v[66:69], v[158:161], v[208:211], v[66:69]
	v_mfma_f32_16x16x32_bf16 v[66:69], v[154:157], v[204:207], v[66:69]
	s_setprio 0
	s_barrier
	s_add_i32 s12, s23, s42
	v_lshl_add_u64 v[212:213], v[212:213], 0, s[62:63]
	s_mov_b32 m0, s12
	ds_read_b128 v[174:177], v198 offset:49152
	ds_read_b128 v[178:181], v198 offset:50176
	ds_read_b128 v[182:185], v198 offset:51200
	ds_read_b128 v[186:189], v198 offset:52224
	ds_read_b128 v[190:193], v198 offset:53248
	ds_read_b128 v[200:203], v198 offset:54272
	ds_read_b128 v[204:207], v198 offset:55296
	ds_read_b128 v[208:211], v198 offset:56320
	global_load_lds_dwordx4 v[212:213], off
	s_add_i32 m0, s12, 0x2000
	s_add_u32 s12, s50, 0x158080
	v_lshl_add_u64 v[212:213], v[232:233], 0, s[62:63]
	s_addc_u32 s13, s51, 0
	s_add_i32 s23, s24, s42
	global_load_lds_dwordx4 v[212:213], off
	v_lshl_add_u64 v[212:213], s[12:13], 0, v[164:165]
	s_mov_b32 m0, s23
	s_nop 0
	global_load_lds_dwordx4 v[212:213], off
	v_lshl_add_u64 v[212:213], s[12:13], 0, v[168:169]
	s_add_i32 m0, s23, 0x2000
	s_nop 0
	global_load_lds_dwordx4 v[212:213], off
	v_lshl_add_u64 v[212:213], v[234:235], 0, s[62:63]
	s_mov_b32 m0, s1
	s_nop 0
	global_load_lds_dwordx4 v[212:213], off
	v_lshl_add_u64 v[212:213], v[236:237], 0, s[62:63]
	s_mov_b32 m0, s52
	s_nop 0
	global_load_lds_dwordx4 v[212:213], off
	s_waitcnt vmcnt(8)
	s_waitcnt lgkmcnt(0)
	s_barrier
	s_setprio 1
	s_waitcnt lgkmcnt(0)
	v_mfma_f32_16x16x32_bf16 v[62:65], v[122:125], v[174:177], v[62:65]
	v_mfma_f32_16x16x32_bf16 v[62:65], v[126:129], v[178:181], v[62:65]
	v_mfma_f32_16x16x32_bf16 v[46:49], v[126:129], v[186:189], v[46:49]
	v_mfma_f32_16x16x32_bf16 v[46:49], v[122:125], v[182:185], v[46:49]
	v_mfma_f32_16x16x32_bf16 v[30:33], v[122:125], v[190:193], v[30:33]
	v_mfma_f32_16x16x32_bf16 v[30:33], v[126:129], v[200:203], v[30:33]
	v_mfma_f32_16x16x32_bf16 v[14:17], v[126:129], v[208:211], v[14:17]
	v_mfma_f32_16x16x32_bf16 v[14:17], v[122:125], v[204:207], v[14:17]
	v_mfma_f32_16x16x32_bf16 v[58:61], v[138:141], v[174:177], v[58:61]
	v_mfma_f32_16x16x32_bf16 v[58:61], v[142:145], v[178:181], v[58:61]
	v_mfma_f32_16x16x32_bf16 v[42:45], v[142:145], v[186:189], v[42:45]
	v_mfma_f32_16x16x32_bf16 v[42:45], v[138:141], v[182:185], v[42:45]
	v_mfma_f32_16x16x32_bf16 v[26:29], v[138:141], v[190:193], v[26:29]
	v_mfma_f32_16x16x32_bf16 v[26:29], v[142:145], v[200:203], v[26:29]
	v_mfma_f32_16x16x32_bf16 v[10:13], v[142:145], v[208:211], v[10:13]
	v_mfma_f32_16x16x32_bf16 v[10:13], v[138:141], v[204:207], v[10:13]
	s_setprio 0
	s_setprio 1
	v_mfma_f32_16x16x32_bf16 v[54:57], v[146:149], v[174:177], v[54:57]
	v_mfma_f32_16x16x32_bf16 v[54:57], v[150:153], v[178:181], v[54:57]
	v_mfma_f32_16x16x32_bf16 v[38:41], v[150:153], v[186:189], v[38:41]
	v_mfma_f32_16x16x32_bf16 v[38:41], v[146:149], v[182:185], v[38:41]
	v_mfma_f32_16x16x32_bf16 v[22:25], v[146:149], v[190:193], v[22:25]
	v_mfma_f32_16x16x32_bf16 v[22:25], v[150:153], v[200:203], v[22:25]
	v_mfma_f32_16x16x32_bf16 v[6:9], v[150:153], v[208:211], v[6:9]
	v_mfma_f32_16x16x32_bf16 v[6:9], v[146:149], v[204:207], v[6:9]
	v_mfma_f32_16x16x32_bf16 v[50:53], v[154:157], v[174:177], v[50:53]
	v_mfma_f32_16x16x32_bf16 v[50:53], v[158:161], v[178:181], v[50:53]
	v_mfma_f32_16x16x32_bf16 v[34:37], v[158:161], v[186:189], v[34:37]
	v_mfma_f32_16x16x32_bf16 v[34:37], v[154:157], v[182:185], v[34:37]
	v_mfma_f32_16x16x32_bf16 v[18:21], v[154:157], v[190:193], v[18:21]
	v_mfma_f32_16x16x32_bf16 v[18:21], v[158:161], v[200:203], v[18:21]
	v_mfma_f32_16x16x32_bf16 v[2:5], v[158:161], v[208:211], v[2:5]
	v_mfma_f32_16x16x32_bf16 v[2:5], v[154:157], v[204:207], v[2:5]
	s_setprio 0
	s_barrier
	s_add_i32 s22, s22, 2
	s_add_u32 s20, s20, 0x100
	s_addc_u32 s21, s21, 0
	s_cmpk_gt_u32 s22, 0x53
	s_mov_b64 s[12:13], s[10:11]
	s_cbranch_scc0 .LBB0_238
	s_and_b64 vcc, exec, s[2:3]
	s_cbranch_vccz .LBB0_241
	s_barrier

.LBB0_340:
	s_add_u32 s22, s46, 0xfff80080
	s_addc_u32 s23, s47, -1
	s_add_i32 s24, 0, 0x10000
	s_cmp_eq_u32 s21, 28
	s_cselect_b32 s51, s1, s23
	s_cselect_b32 s50, s13, s22
	v_add_u32_e32 v148, s24, v152
	s_cselect_b32 s49, s11, s20
	s_cselect_b32 s48, s18, s19
	s_add_i32 s25, 0, 0x14000
	ds_read_b128 v[144:147], v148
	ds_read_b128 v[156:159], v148 offset:1024
	ds_read_b128 v[160:163], v148 offset:2048
	ds_read_b128 v[164:167], v148 offset:3072
	v_add_u32_e32 v148, s25, v152
	ds_read_b128 v[168:171], v148
	ds_read_b128 v[172:175], v148 offset:1024
	ds_read_b128 v[176:179], v148 offset:2048
	ds_read_b128 v[180:183], v148 offset:3072
	v_lshl_add_u64 v[148:149], s[46:47], 0, v[140:141]
	s_add_i32 m0, s3, 0xc000
	ds_read_b128 v[184:187], v154
	ds_read_b128 v[188:191], v154 offset:1024
	ds_read_b128 v[192:195], v154 offset:2048
	ds_read_b128 v[196:199], v154 offset:3072
	ds_read_b128 v[200:203], v154 offset:4096
	ds_read_b128 v[204:207], v154 offset:5120
	ds_read_b128 v[208:211], v154 offset:6144
	ds_read_b128 v[232:235], v154 offset:7168
	global_load_lds_dwordx4 v[148:149], off
	v_lshl_add_u64 v[148:149], s[46:47], 0, v[142:143]
	s_add_i32 m0, s3, 0xe000
	s_nop 0
	global_load_lds_dwordx4 v[148:149], off
	s_waitcnt vmcnt(8)
	s_waitcnt lgkmcnt(0)
	s_barrier
	s_setprio 1
	s_waitcnt lgkmcnt(0)
	v_mfma_f32_16x16x32_bf16 v[126:129], v[144:147], v[184:187], v[126:129]
	v_mfma_f32_16x16x32_bf16 v[126:129], v[156:159], v[188:191], v[126:129]
	v_mfma_f32_16x16x32_bf16 v[110:113], v[156:159], v[196:199], v[110:113]
	v_mfma_f32_16x16x32_bf16 v[110:113], v[144:147], v[192:195], v[110:113]
	v_mfma_f32_16x16x32_bf16 v[94:97], v[144:147], v[200:203], v[94:97]
	v_mfma_f32_16x16x32_bf16 v[94:97], v[156:159], v[204:207], v[94:97]
	v_mfma_f32_16x16x32_bf16 v[78:81], v[156:159], v[232:235], v[78:81]
	v_mfma_f32_16x16x32_bf16 v[78:81], v[144:147], v[208:211], v[78:81]
	v_mfma_f32_16x16x32_bf16 v[122:125], v[160:163], v[184:187], v[122:125]
	v_mfma_f32_16x16x32_bf16 v[122:125], v[164:167], v[188:191], v[122:125]
	v_mfma_f32_16x16x32_bf16 v[106:109], v[164:167], v[196:199], v[106:109]
	v_mfma_f32_16x16x32_bf16 v[106:109], v[160:163], v[192:195], v[106:109]
	v_mfma_f32_16x16x32_bf16 v[90:93], v[160:163], v[200:203], v[90:93]
	v_mfma_f32_16x16x32_bf16 v[90:93], v[164:167], v[204:207], v[90:93]
	v_mfma_f32_16x16x32_bf16 v[74:77], v[164:167], v[232:235], v[74:77]
	v_mfma_f32_16x16x32_bf16 v[74:77], v[160:163], v[208:211], v[74:77]
	s_setprio 0
	s_setprio 1
	v_mfma_f32_16x16x32_bf16 v[118:121], v[168:171], v[184:187], v[118:121]
	v_mfma_f32_16x16x32_bf16 v[118:121], v[172:175], v[188:191], v[118:121]
	v_mfma_f32_16x16x32_bf16 v[102:105], v[172:175], v[196:199], v[102:105]
	v_mfma_f32_16x16x32_bf16 v[102:105], v[168:171], v[192:195], v[102:105]
	v_mfma_f32_16x16x32_bf16 v[86:89], v[168:171], v[200:203], v[86:89]
	v_mfma_f32_16x16x32_bf16 v[86:89], v[172:175], v[204:207], v[86:89]
	v_mfma_f32_16x16x32_bf16 v[70:73], v[172:175], v[232:235], v[70:73]
	v_mfma_f32_16x16x32_bf16 v[70:73], v[168:171], v[208:211], v[70:73]
	v_mfma_f32_16x16x32_bf16 v[114:117], v[176:179], v[184:187], v[114:117]
	v_mfma_f32_16x16x32_bf16 v[114:117], v[180:183], v[188:191], v[114:117]
	v_mfma_f32_16x16x32_bf16 v[98:101], v[180:183], v[196:199], v[98:101]
	v_mfma_f32_16x16x32_bf16 v[98:101], v[176:179], v[192:195], v[98:101]
	v_mfma_f32_16x16x32_bf16 v[82:85], v[176:179], v[200:203], v[82:85]
	v_mfma_f32_16x16x32_bf16 v[82:85], v[180:183], v[204:207], v[82:85]
	v_mfma_f32_16x16x32_bf16 v[66:69], v[180:183], v[232:235], v[66:69]
	v_mfma_f32_16x16x32_bf16 v[66:69], v[176:179], v[208:211], v[66:69]
	s_setprio 0
	s_barrier
	s_add_i32 s22, s24, s16
	v_lshl_add_u64 v[148:149], s[48:49], 0, v[134:135]
	s_mov_b32 m0, s22
	ds_read_b128 v[184:187], v154 offset:16384
	ds_read_b128 v[188:191], v154 offset:17408
	ds_read_b128 v[192:195], v154 offset:18432
	ds_read_b128 v[196:199], v154 offset:19456
	ds_read_b128 v[200:203], v154 offset:20480
	ds_read_b128 v[204:207], v154 offset:21504
	ds_read_b128 v[208:211], v154 offset:22528
	ds_read_b128 v[232:235], v154 offset:23552
	global_load_lds_dwordx4 v[148:149], off
	s_add_i32 m0, s22, 0x2000
	s_add_u32 s22, s48, 0x80000
	v_lshl_add_u64 v[212:213], s[48:49], 0, v[130:131]
	s_addc_u32 s23, s49, 0
	s_add_i32 s24, s25, s16
	global_load_lds_dwordx4 v[212:213], off
	v_lshl_add_u64 v[236:237], s[22:23], 0, v[134:135]
	s_mov_b32 m0, s24
	v_lshl_add_u64 v[238:239], s[50:51], 0, v[132:133]
	global_load_lds_dwordx4 v[236:237], off
	v_lshl_add_u64 v[236:237], s[22:23], 0, v[130:131]
	s_add_i32 m0, s24, 0x2000
	s_nop 0
	global_load_lds_dwordx4 v[236:237], off
	v_lshl_add_u64 v[236:237], s[50:51], 0, v[136:137]
	s_mov_b32 m0, s3
	s_nop 0
	global_load_lds_dwordx4 v[236:237], off
	s_mov_b32 m0, s55
	s_nop 0
	global_load_lds_dwordx4 v[238:239], off
	s_waitcnt vmcnt(8)
	s_waitcnt lgkmcnt(0)
	s_barrier
	s_setprio 1
	s_waitcnt lgkmcnt(0)
	v_mfma_f32_16x16x32_bf16 v[62:65], v[144:147], v[184:187], v[62:65]
	v_mfma_f32_16x16x32_bf16 v[62:65], v[156:159], v[188:191], v[62:65]
	v_mfma_f32_16x16x32_bf16 v[46:49], v[156:159], v[196:199], v[46:49]
	v_mfma_f32_16x16x32_bf16 v[46:49], v[144:147], v[192:195], v[46:49]
	v_mfma_f32_16x16x32_bf16 v[30:33], v[144:147], v[200:203], v[30:33]
	v_mfma_f32_16x16x32_bf16 v[30:33], v[156:159], v[204:207], v[30:33]
	v_mfma_f32_16x16x32_bf16 v[14:17], v[156:159], v[232:235], v[14:17]
	v_mfma_f32_16x16x32_bf16 v[14:17], v[144:147], v[208:211], v[14:17]
	v_mfma_f32_16x16x32_bf16 v[58:61], v[160:163], v[184:187], v[58:61]
	v_mfma_f32_16x16x32_bf16 v[58:61], v[164:167], v[188:191], v[58:61]
	v_mfma_f32_16x16x32_bf16 v[42:45], v[164:167], v[196:199], v[42:45]
	v_mfma_f32_16x16x32_bf16 v[42:45], v[160:163], v[192:195], v[42:45]
	v_mfma_f32_16x16x32_bf16 v[26:29], v[160:163], v[200:203], v[26:29]
	v_mfma_f32_16x16x32_bf16 v[26:29], v[164:167], v[204:207], v[26:29]
	v_mfma_f32_16x16x32_bf16 v[10:13], v[164:167], v[232:235], v[10:13]
	v_mfma_f32_16x16x32_bf16 v[10:13], v[160:163], v[208:211], v[10:13]
	s_setprio 0
	s_setprio 1
	v_mfma_f32_16x16x32_bf16 v[54:57], v[168:171], v[184:187], v[54:57]
	v_mfma_f32_16x16x32_bf16 v[54:57], v[172:175], v[188:191], v[54:57]
	v_mfma_f32_16x16x32_bf16 v[38:41], v[172:175], v[196:199], v[38:41]
	v_mfma_f32_16x16x32_bf16 v[38:41], v[168:171], v[192:195], v[38:41]
	v_mfma_f32_16x16x32_bf16 v[22:25], v[168:171], v[200:203], v[22:25]
	v_mfma_f32_16x16x32_bf16 v[22:25], v[172:175], v[204:207], v[22:25]
	v_mfma_f32_16x16x32_bf16 v[6:9], v[172:175], v[232:235], v[6:9]
	v_mfma_f32_16x16x32_bf16 v[6:9], v[168:171], v[208:211], v[6:9]
	v_mfma_f32_16x16x32_bf16 v[50:53], v[176:179], v[184:187], v[50:53]
	v_mfma_f32_16x16x32_bf16 v[50:53], v[180:183], v[188:191], v[50:53]
	v_mfma_f32_16x16x32_bf16 v[34:37], v[180:183], v[196:199], v[34:37]
	v_mfma_f32_16x16x32_bf16 v[34:37], v[176:179], v[192:195], v[34:37]
	v_mfma_f32_16x16x32_bf16 v[18:21], v[176:179], v[200:203], v[18:21]
	v_mfma_f32_16x16x32_bf16 v[18:21], v[180:183], v[204:207], v[18:21]
	v_mfma_f32_16x16x32_bf16 v[2:5], v[180:183], v[232:235], v[2:5]
	v_mfma_f32_16x16x32_bf16 v[2:5], v[176:179], v[208:211], v[2:5]
	s_setprio 0
	s_barrier
	s_add_i32 s24, 0, 0x18000
	v_add_u32_e32 v155, s24, v152
	s_add_i32 s25, 0, 0x1c000
	ds_read_b128 v[144:147], v155
	ds_read_b128 v[156:159], v155 offset:1024
	ds_read_b128 v[160:163], v155 offset:2048
	ds_read_b128 v[164:167], v155 offset:3072
	v_add_u32_e32 v155, s25, v152
	ds_read_b128 v[168:171], v155
	ds_read_b128 v[172:175], v155 offset:1024
	ds_read_b128 v[176:179], v155 offset:2048
	ds_read_b128 v[180:183], v155 offset:3072
	s_add_u32 s22, s50, 0x80000
	s_addc_u32 s23, s51, 0
	s_mov_b32 m0, s57
	v_lshl_add_u64 v[240:241], s[22:23], 0, v[136:137]
	ds_read_b128 v[184:187], v154 offset:32768
	ds_read_b128 v[188:191], v154 offset:33792
	ds_read_b128 v[192:195], v154 offset:34816
	ds_read_b128 v[196:199], v154 offset:35840
	ds_read_b128 v[200:203], v154 offset:36864
	ds_read_b128 v[204:207], v154 offset:37888
	ds_read_b128 v[208:211], v154 offset:38912
	ds_read_b128 v[232:235], v154 offset:39936
	global_load_lds_dwordx4 v[240:241], off
	v_lshl_add_u64 v[240:241], s[22:23], 0, v[132:133]
	s_mov_b32 m0, s68
	s_nop 0
	global_load_lds_dwordx4 v[240:241], off
	s_waitcnt vmcnt(8)
	s_waitcnt lgkmcnt(0)
	s_barrier
	s_setprio 1
	s_waitcnt lgkmcnt(0)
	v_mfma_f32_16x16x32_bf16 v[126:129], v[144:147], v[184:187], v[126:129]
	v_mfma_f32_16x16x32_bf16 v[126:129], v[156:159], v[188:191], v[126:129]
	v_mfma_f32_16x16x32_bf16 v[110:113], v[156:159], v[196:199], v[110:113]
	v_mfma_f32_16x16x32_bf16 v[110:113], v[144:147], v[192:195], v[110:113]
	v_mfma_f32_16x16x32_bf16 v[94:97], v[144:147], v[200:203], v[94:97]
	v_mfma_f32_16x16x32_bf16 v[94:97], v[156:159], v[204:207], v[94:97]
	v_mfma_f32_16x16x32_bf16 v[78:81], v[156:159], v[232:235], v[78:81]
	v_mfma_f32_16x16x32_bf16 v[78:81], v[144:147], v[208:211], v[78:81]
	v_mfma_f32_16x16x32_bf16 v[122:125], v[160:163], v[184:187], v[122:125]
	v_mfma_f32_16x16x32_bf16 v[122:125], v[164:167], v[188:191], v[122:125]
	v_mfma_f32_16x16x32_bf16 v[106:109], v[164:167], v[196:199], v[106:109]
	v_mfma_f32_16x16x32_bf16 v[106:109], v[160:163], v[192:195], v[106:109]
	v_mfma_f32_16x16x32_bf16 v[90:93], v[160:163], v[200:203], v[90:93]
	v_mfma_f32_16x16x32_bf16 v[90:93], v[164:167], v[204:207], v[90:93]
	v_mfma_f32_16x16x32_bf16 v[74:77], v[164:167], v[232:235], v[74:77]
	v_mfma_f32_16x16x32_bf16 v[74:77], v[160:163], v[208:211], v[74:77]
	s_setprio 0
	s_setprio 1
	v_mfma_f32_16x16x32_bf16 v[118:121], v[168:171], v[184:187], v[118:121]
	v_mfma_f32_16x16x32_bf16 v[118:121], v[172:175], v[188:191], v[118:121]
	v_mfma_f32_16x16x32_bf16 v[102:105], v[172:175], v[196:199], v[102:105]
	v_mfma_f32_16x16x32_bf16 v[102:105], v[168:171], v[192:195], v[102:105]
	v_mfma_f32_16x16x32_bf16 v[86:89], v[168:171], v[200:203], v[86:89]
	v_mfma_f32_16x16x32_bf16 v[86:89], v[172:175], v[204:207], v[86:89]
	v_mfma_f32_16x16x32_bf16 v[70:73], v[172:175], v[232:235], v[70:73]
	v_mfma_f32_16x16x32_bf16 v[70:73], v[168:171], v[208:211], v[70:73]
	v_mfma_f32_16x16x32_bf16 v[114:117], v[176:179], v[184:187], v[114:117]
	v_mfma_f32_16x16x32_bf16 v[114:117], v[180:183], v[188:191], v[114:117]
	v_mfma_f32_16x16x32_bf16 v[98:101], v[180:183], v[196:199], v[98:101]
	v_mfma_f32_16x16x32_bf16 v[98:101], v[176:179], v[192:195], v[98:101]
	v_mfma_f32_16x16x32_bf16 v[82:85], v[176:179], v[200:203], v[82:85]
	v_mfma_f32_16x16x32_bf16 v[82:85], v[180:183], v[204:207], v[82:85]
	v_mfma_f32_16x16x32_bf16 v[66:69], v[180:183], v[232:235], v[66:69]
	v_mfma_f32_16x16x32_bf16 v[66:69], v[176:179], v[208:211], v[66:69]
	s_setprio 0
	s_barrier
	s_add_i32 s22, s24, s16
	v_lshl_add_u64 v[148:149], v[148:149], 0, s[62:63]
	s_mov_b32 m0, s22
	ds_read_b128 v[184:187], v154 offset:49152
	ds_read_b128 v[188:191], v154 offset:50176
	ds_read_b128 v[192:195], v154 offset:51200
	ds_read_b128 v[196:199], v154 offset:52224
	ds_read_b128 v[200:203], v154 offset:53248
	ds_read_b128 v[204:207], v154 offset:54272
	ds_read_b128 v[208:211], v154 offset:55296
	ds_read_b128 v[232:235], v154 offset:56320
	global_load_lds_dwordx4 v[148:149], off
	s_add_i32 m0, s22, 0x2000
	s_add_u32 s22, s48, 0x80080
	v_lshl_add_u64 v[148:149], v[212:213], 0, s[62:63]
	s_addc_u32 s23, s49, 0
	s_add_i32 s24, s25, s16
	global_load_lds_dwordx4 v[148:149], off
	v_lshl_add_u64 v[148:149], s[22:23], 0, v[134:135]
	s_mov_b32 m0, s24
	s_nop 0
	global_load_lds_dwordx4 v[148:149], off
	v_lshl_add_u64 v[148:149], s[22:23], 0, v[130:131]
	s_add_i32 m0, s24, 0x2000
	s_nop 0
	global_load_lds_dwordx4 v[148:149], off
	v_lshl_add_u64 v[148:149], v[236:237], 0, s[62:63]
	s_mov_b32 m0, s69
	s_nop 0
	global_load_lds_dwordx4 v[148:149], off
	v_lshl_add_u64 v[148:149], v[238:239], 0, s[62:63]
	s_mov_b32 m0, s70
	s_nop 0
	global_load_lds_dwordx4 v[148:149], off
	s_waitcnt vmcnt(8)
	s_waitcnt lgkmcnt(0)
	s_barrier
	s_setprio 1
	s_waitcnt lgkmcnt(0)
	v_mfma_f32_16x16x32_bf16 v[62:65], v[144:147], v[184:187], v[62:65]
	v_mfma_f32_16x16x32_bf16 v[62:65], v[156:159], v[188:191], v[62:65]
	v_mfma_f32_16x16x32_bf16 v[46:49], v[156:159], v[196:199], v[46:49]
	v_mfma_f32_16x16x32_bf16 v[46:49], v[144:147], v[192:195], v[46:49]
	v_mfma_f32_16x16x32_bf16 v[30:33], v[144:147], v[200:203], v[30:33]
	v_mfma_f32_16x16x32_bf16 v[30:33], v[156:159], v[204:207], v[30:33]
	v_mfma_f32_16x16x32_bf16 v[14:17], v[156:159], v[232:235], v[14:17]
	v_mfma_f32_16x16x32_bf16 v[14:17], v[144:147], v[208:211], v[14:17]
	v_mfma_f32_16x16x32_bf16 v[58:61], v[160:163], v[184:187], v[58:61]
	v_mfma_f32_16x16x32_bf16 v[58:61], v[164:167], v[188:191], v[58:61]
	v_mfma_f32_16x16x32_bf16 v[42:45], v[164:167], v[196:199], v[42:45]
	v_mfma_f32_16x16x32_bf16 v[42:45], v[160:163], v[192:195], v[42:45]
	v_mfma_f32_16x16x32_bf16 v[26:29], v[160:163], v[200:203], v[26:29]
	v_mfma_f32_16x16x32_bf16 v[26:29], v[164:167], v[204:207], v[26:29]
	v_mfma_f32_16x16x32_bf16 v[10:13], v[164:167], v[232:235], v[10:13]
	v_mfma_f32_16x16x32_bf16 v[10:13], v[160:163], v[208:211], v[10:13]
	s_setprio 0
	s_setprio 1
	v_mfma_f32_16x16x32_bf16 v[54:57], v[168:171], v[184:187], v[54:57]
	v_mfma_f32_16x16x32_bf16 v[54:57], v[172:175], v[188:191], v[54:57]
	v_mfma_f32_16x16x32_bf16 v[38:41], v[172:175], v[196:199], v[38:41]
	v_mfma_f32_16x16x32_bf16 v[38:41], v[168:171], v[192:195], v[38:41]
	v_mfma_f32_16x16x32_bf16 v[22:25], v[168:171], v[200:203], v[22:25]
	v_mfma_f32_16x16x32_bf16 v[22:25], v[172:175], v[204:207], v[22:25]
	v_mfma_f32_16x16x32_bf16 v[6:9], v[172:175], v[232:235], v[6:9]
	v_mfma_f32_16x16x32_bf16 v[6:9], v[168:171], v[208:211], v[6:9]
	v_mfma_f32_16x16x32_bf16 v[50:53], v[176:179], v[184:187], v[50:53]
	v_mfma_f32_16x16x32_bf16 v[50:53], v[180:183], v[188:191], v[50:53]
	v_mfma_f32_16x16x32_bf16 v[34:37], v[180:183], v[196:199], v[34:37]
	v_mfma_f32_16x16x32_bf16 v[34:37], v[176:179], v[192:195], v[34:37]
	v_mfma_f32_16x16x32_bf16 v[18:21], v[176:179], v[200:203], v[18:21]
	v_mfma_f32_16x16x32_bf16 v[18:21], v[180:183], v[204:207], v[18:21]
	v_mfma_f32_16x16x32_bf16 v[2:5], v[180:183], v[232:235], v[2:5]
	v_mfma_f32_16x16x32_bf16 v[2:5], v[176:179], v[208:211], v[2:5]
	s_setprio 0
	s_barrier
	s_add_i32 s21, s21, 2
	s_add_u32 s46, s46, 0x100
	s_addc_u32 s47, s47, 0
	s_add_u32 s19, s19, 0x100
	s_addc_u32 s20, s20, 0
	s_cmp_gt_u32 s21, 29
	s_cbranch_scc0 .LBB0_340
	s_and_b64 vcc, exec, s[8:9]
	s_cbranch_vccz .LBB0_343
	s_barrier
